# P7 start: touch first two K-tiles of the workgroup's first P8 weight tile (one dword per line)
# baseline (speedup 1.0000x reference)
; #define PHASE_IDS() int tid_l = threadIdx.x; asm volatile("" : "+v"(tid_l)); const int lane = tid_l & 63, wave = __builtin_amdgcn_readfirstlane(tid_l >> 6), gw = vcu * NWAVES + wave; (void)lane; (void)gw
; __global__ void __launch_bounds__(NWAVES * 64, 2) hymba_fwd(Args a) {
;     ...
;         PHASE_IDS();
;         float* RH = (float*)(ws + WS_RH); const float* RX = (const float*)(ws + WS_RX);
;         f32x4 gq[8];
; #pragma unroll
;         for (int j = 0; j < 4; ++j) { gq[2 * j] = ((const f32x4*)a.g_post_mix)[128 * j + 2 * lane]; gq[2 * j + 1] = ((const f32x4*)a.g_post_mix)[128 * j + 2 * lane + 1]; }
;         for (int it = 0; it < 4; ++it) { const int mb = team_pm * 256 + team_k * 64 + wave * 8 + it * 2;
;             v4u mv[2][4], xv[2][4]; float rxi[2], sm[2];
; #pragma unroll
;             for (int q = 0; q < 2; ++q) { const v4u* mr = (const v4u*)(MIX + (size_t)(mb + q) * DM); const v4u* xr = (const v4u*)(R1 + (size_t)(mb + q) * DM); rxi[q] = RX[mb + q];
.LBB0_867:
	s_or_b64 exec, exec, s[0:1]
	v_mov_b32_e32 v38, v0
	v_readlane_b32 s16, v254, 21
	s_barrier
	s_lshr_b32 s2, s74, 6
	s_lshl_b32 s2, s2, 20
	s_add_u32 s0, s94, s2
	s_addc_u32 s1, s95, 0
	s_add_u32 s0, s0, 0x1600000
	s_addc_u32 s1, s1, 0
	v_and_b32_e32 v200, 0xff, v38
	v_lshlrev_b32_e32 v200, 12, v200
	v_lshrrev_b32_e32 v201, 8, v38
	v_lshl_or_b32 v200, v201, 7, v200
	global_load_dword v202, v200, s[0:1]
	v_readlane_b32 s20, v254, 25
	v_and_b32_e32 v39, 63, v38
	v_readlane_b32 s21, v254, 26
	v_lshlrev_b32_e32 v18, 5, v39
	v_mov_b32_e32 v19, 0
	s_mov_b64 s[4:5], s[20:21]
	v_lshl_add_u64 v[26:27], s[4:5], 0, v[18:19]
	s_mov_b64 s[0:1], 0x1000
	v_lshl_add_u64 v[28:29], v[26:27], 0, s[0:1]
	s_movk_i32 s0, 0x1000
	global_load_dwordx4 v[2:5], v18, s[20:21]
	global_load_dwordx4 v[6:9], v18, s[20:21] offset:16
	global_load_dwordx4 v[10:13], v18, s[20:21] offset:2048
	global_load_dwordx4 v[14:17], v18, s[20:21] offset:2064
	v_add_co_u32_e32 v34, vcc, s0, v26
	s_mov_b64 s[0:1], 0x1800
	s_nop 0
	v_addc_co_u32_e32 v35, vcc, 0, v27, vcc
	global_load_dwordx4 v[18:21], v[34:35], off
	global_load_dwordx4 v[22:25], v[28:29], off offset:16
	v_lshl_add_u64 v[36:37], v[26:27], 0, s[0:1]
	global_load_dwordx4 v[26:29], v[34:35], off offset:2048
	global_load_dwordx4 v[30:33], v[36:37], off offset:16
	v_xor_b32_e32 v34, 1, v1
	v_cmp_lt_i32_e32 vcc, v34, v173
	s_and_b32 s4, s74, 7
	v_readlane_b32 s5, v254, 4
	v_cndmask_b32_e32 v34, v1, v34, vcc
	v_lshlrev_b32_e32 v148, 2, v34
	v_xor_b32_e32 v34, 2, v1
	v_cmp_lt_i32_e32 vcc, v34, v173
	v_readfirstlane_b32 s0, v38
	s_lshl_b32 s4, s4, 11
	v_cndmask_b32_e32 v34, v1, v34, vcc
	v_lshlrev_b32_e32 v149, 2, v34
	v_xor_b32_e32 v34, 4, v1
	v_cmp_lt_i32_e32 vcc, v34, v173
	s_lshl_b32 s5, s5, 8
	s_and_b32 s38, s74, 0xffffffc0
	v_cndmask_b32_e32 v34, v1, v34, vcc
	v_lshlrev_b32_e32 v150, 2, v34
	v_xor_b32_e32 v34, 8, v1
	s_ashr_i32 s0, s0, 3
	v_cmp_lt_i32_e32 vcc, v34, v173
	s_or_b32 s4, s4, s5
	s_and_b32 s2, s0, -8
	v_cndmask_b32_e32 v34, v1, v34, vcc
	s_add_i32 s4, s4, s38
	v_lshlrev_b32_e32 v151, 2, v34
	v_xor_b32_e32 v34, 16, v1
	s_add_i32 s4, s4, s2
	v_cmp_lt_i32_e32 vcc, v34, v173
	s_ashr_i32 s5, s4, 31
	v_readlane_b32 s17, v254, 22
	v_readlane_b32 s18, v254, 23
	v_readlane_b32 s19, v254, 24
	v_readlane_b32 s22, v254, 27
	v_readlane_b32 s23, v254, 28
	v_readlane_b32 s24, v254, 29
	v_readlane_b32 s25, v254, 30
	v_readlane_b32 s26, v254, 31
	v_readlane_b32 s27, v254, 32
	v_readlane_b32 s28, v254, 33
	v_readlane_b32 s29, v254, 34
	v_readlane_b32 s30, v254, 35
	v_readlane_b32 s31, v254, 36
	v_cndmask_b32_e32 v1, v1, v34, vcc
	s_lshl_b64 s[14:15], s[4:5], 2
	s_lshl_b64 s[4:5], s[4:5], 12
	s_mov_b32 s3, 4
	v_lshlrev_b32_e32 v152, 2, v1
	v_cmp_eq_u32_e64 s[0:1], 0, v39
	v_lshl_or_b32 v70, v39, 4, s4
	v_mov_b32_e32 v71, s5
	v_mov_b32_e32 v1, 0x6e00000
	s_mov_b64 s[16:17], 0x7000000
	s_mov_b64 s[18:19], 0x7000400
	s_mov_b64 s[20:21], 0x7000800
	s_mov_b64 s[22:23], 0x7000c00
	s_mov_b32 s4, 0xb001000
	s_mov_b64 s[24:25], 0x7001000
	s_mov_b32 s5, 0x7001000
	s_mov_b64 s[26:27], 0x7001400
	s_mov_b64 s[28:29], 0x7001800
	s_mov_b64 s[30:31], 0x7001c00
	v_mov_b32_e32 v127, 0x358637bd
	s_mov_b32 s39, 0xf800000
	v_mov_b32_e32 v128, 0x260
	v_mov_b32_e32 v129, 0x6d00000
	s_mov_b64 s[34:35], 0x2000
	s_branch .LBB0_869
